# NA+conv phase: waves 4-7 run their conv items before their attention tasks (SIMD partners no longer run the same kind of stream at the same time)
# speedup vs baseline: 1.0130x; 1.0001x over previous
; #define REP(k) for (int rep_ = 0; rep_ < (((REPMASK) >> (k)) & 1) + 1; ++rep_)
; __device__ __forceinline__ void na_task(const P& p, int task, int lane, float* ldsw  ) {
;     const int fr = lane & 15, g = lane >> 4;
;     const bf16_t* QK = (const bf16_t*)(p.ws + WS_NAQK); const bf16_t* VT = (const bf16_t*)(p.ws + WS_NAVT); bf16_t* Y = (bf16_t*)(p.ws + WS_A);
;     if (task < 2048) {
;         const int h = task & 7, r = (task >> 3) & 31, b = task >> 8;
;         for (int i = lane; i < 465; i += 64) ldsw[i] = p.rpb[h * 465 + i];
;         AttnState st[4];
;         bf16_t* qlds = (bf16_t*)(ldsw + 512) + fr * 72 + g * 8;
;         const size_t qrow0 = (size_t)b * TLAT + r * 64 + fr;
; #pragma unroll
;         for (int j = 0; j < 4; ++j) {
;             st[j].m = -1e30f; st[j].l = 0.f;
; #pragma unroll
;             for (int dt = 0; dt < 4; ++dt) st[j].o[dt] = (f32x4){0.f, 0.f, 0.f, 0.f};
;             const bf16_t* qp = QK + (qrow0 + j * 16) * 1024 + h * 64 + g * 8;
;             *(bf16x8*)(qlds + j * 16 * 72) = *(const bf16x8*)qp; *(bf16x8*)(qlds + j * 16 * 72 + 32) = *(const bf16x8*)(qp + 32);
;         }
;         const int r0 = clampi(r - 4, 0, 24);
;         const bf16_t* vb = VT + ((size_t)b * 512 + h * 64) * TT;
;         const bf16_t* kbase = QK + 512 + h * 64 + g * 8;
;         auto ldk = [&](int i, AttnKn& k) {
; __global__ void __launch_bounds__(NTHREADS) mega_fwd(P p) {
;     ...
;                 PH();
;                 {
;                     const int vcu = (G % 8 == 0) ? ((int)blockIdx.x % 8) * (G / 8) + (int)blockIdx.x / 8 : (int)blockIdx.x;
;                     if (RUN(5)) REP(5) for (int t = vcu * 8 + wave; t < 3072; t += ngw) na_task(q, t, lane, (float*)(lds + wave * 12288));
;                 }
;                 PH();
;                 if (ngw == 2048) {
;                     const int vcu = ((int)blockIdx.x % 8) * (G / 8) + (int)blockIdx.x / 8, gwv = vcu * 8 + wave;
;                     if (RUN(6)) REP(6) {
;                         if (gwv >= 1024) { for (int k = 0; k < 4; ++k) dn_conv_token4(q, ((gwv - 1024) * 4 + k) * 4, lane); }
;                         else if (gwv < 512) dn_conv_token4(q, (4096 + gwv) * 4, lane);
;                     }
;                 } else if (RUN(6)) REP(6) for (int m = gw * 4; m < MALL; m += ngw * 4) dn_conv_token4(q, m, lane);
.LBB0_378:
	s_or_b64 exec, exec, s[2:3]
	v_mov_b32_e32 v0, v1
	s_waitcnt lgkmcnt(0)
	s_barrier
	v_readfirstlane_b32 s100, v144
	s_lshr_b32 s100, s100, 8
	s_cmp_eq_u32 s100, 0
	s_cbranch_scc1 .Lst_na
	s_branch .LBB0_418
.Lst_na:
	v_readlane_b32 s2, v254, 18
	v_readfirstlane_b32 s49, v144
	s_ashr_i32 s48, s49, 6
	s_add_i32 s84, s2, s48
	s_cmpk_gt_i32 s84, 0xbff
	v_readfirstlane_b32 s2, v0
	s_cbranch_scc1 .LBB0_418
	s_load_dwordx2 s[44:45], s[92:93], s2 offset:0x58
	s_load_dwordx2 s[46:47], s[92:93], s2 offset:0xa8
	s_mul_i32 s2, s48, 0x3000
	v_and_b32_e32 v2, 48, v144
	v_mov_b32_e32 v3, v1
	s_add_i32 s85, s2, 0
	v_and_b32_e32 v114, 15, v144
	s_waitcnt lgkmcnt(0)
	v_lshl_add_u64 v[4:5], s[46:47], 0, v[2:3]
	s_mov_b64 s[6:7], 0x7f00400
	s_add_u32 s2, s46, 0x7f00000
	v_lshl_add_u64 v[116:117], v[4:5], 0, s[6:7]
	v_mul_u32_u24_e32 v4, 0x90, v114
	v_bfe_u32 v6, v144, 4, 2
	s_addc_u32 s3, s47, 0
	v_add3_u32 v143, s85, v4, v2
	v_subrev_co_u32_e32 v4, vcc, 8, v114
	s_add_u32 s86, s46, 0xa300000
	v_min_u32_e32 v4, 48, v4
	v_lshlrev_b32_e32 v124, 2, v6
	s_addc_u32 s87, s47, 0
	v_cndmask_b32_e64 v8, v4, 0, vcc
	v_or_b32_e32 v170, 16, v124
	s_add_u32 s76, s46, 0x5b00000
	v_add_u32_e32 v9, 16, v8
	v_cmp_lt_u32_e64 s[8:9], v124, v8
	v_cmp_ge_u32_e32 vcc, v170, v8
	v_or_b32_e32 v172, 17, v124
	s_addc_u32 s77, s47, 0
	s_and_b64 s[14:15], vcc, s[8:9]
	v_cmp_ge_u32_e32 vcc, v172, v8
	v_cmp_lt_u32_e64 s[16:17], v172, v9
	v_or_b32_e32 v174, 18, v124
	v_and_b32_e32 v7, 63, v144
	v_or_b32_e32 v167, 1, v124
	v_or_b32_e32 v168, 3, v124
	v_or_b32_e32 v169, 2, v124
	v_sub_u32_e32 v10, v170, v114
	s_and_b64 s[16:17], vcc, s[16:17]
	v_cmp_ge_u32_e32 vcc, v174, v8
	v_cmp_lt_u32_e64 s[18:19], v174, v9
	v_or_b32_e32 v176, 19, v124
	v_or_b32_e32 v5, 48, v7
	v_cmp_lt_u32_e64 s[6:7], v167, v8
	v_cmp_lt_u32_e64 s[10:11], v168, v8
	v_cmp_lt_u32_e64 s[12:13], v169, v8
	v_min_u32_e32 v171, 15, v10
	v_sub_u32_e32 v10, v172, v114
	s_and_b64 s[18:19], vcc, s[18:19]
	v_cmp_ge_u32_e32 vcc, v176, v8
	v_sub_u32_e32 v8, v176, v114
	v_min_u32_e32 v173, 15, v10
	v_sub_u32_e32 v10, v174, v114
	v_min_u32_e32 v177, 15, v8
	v_add_u32_e32 v8, -8, v5
	v_min_u32_e32 v175, 15, v10
	v_min_u32_e32 v8, 48, v8
	v_or_b32_e32 v10, 32, v124
	v_cmp_lt_u32_e64 s[22:23], v10, v8
	v_sub_u32_e32 v10, v10, v5
	v_sub_u32_e64 v183, v10, -15 clamp
	v_or_b32_e32 v10, 33, v124
	v_cmp_lt_u32_e64 s[24:25], v10, v8
	v_sub_u32_e32 v10, v10, v5
	v_sub_u32_e64 v207, v10, -15 clamp
	v_or_b32_e32 v10, 34, v124
	v_cmp_lt_u32_e64 s[26:27], v10, v8
	v_sub_u32_e32 v10, v10, v5
	s_bfe_u32 s49, s49, 0x30006
	v_sub_u32_e64 v208, v10, -15 clamp
	v_or_b32_e32 v10, 35, v124
	v_lshl_add_u64 v[2:3], s[2:3], 0, v[2:3]
	s_lshl_b32 s64, s49, 7
	v_cmp_lt_u32_e64 s[20:21], v176, v9
	v_add_u32_e32 v9, 16, v8
	v_cmp_lt_u32_e64 s[28:29], v10, v8
	v_sub_u32_e32 v8, v10, v5
	v_lshl_add_u64 v[126:127], v[2:3], 0, s[64:65]
	v_lshrrev_b32_e32 v2, 1, v144
	v_sub_u32_e64 v209, v8, -15 clamp
	v_or_b32_e32 v8, 49, v124
	v_or_b32_e32 v10, 48, v124
	v_and_b32_e32 v2, 24, v2
	v_mov_b32_e32 v3, v1
	v_lshlrev_b32_e32 v0, 3, v6
	v_sub_u32_e32 v210, v10, v5
	v_cmp_lt_u32_e64 s[30:31], v8, v9
	v_cmp_lt_u32_e64 s[34:35], v10, v9
	v_or_b32_e32 v8, 51, v124
	v_or_b32_e32 v10, 50, v124
	s_mul_i32 s50, s49, 0x1d1
	v_lshl_add_u64 v[132:133], s[46:47], 0, v[2:3]
	v_readlane_b32 s46, v254, 19
	v_mul_u32_u24_e32 v118, 0x1200, v114
	v_or_b32_e32 v4, 0x800, v124
	v_or_b32_e32 v6, 0x810, v124
	v_cmp_lt_u32_e64 s[40:41], v8, v9
	v_cmp_lt_u32_e64 s[42:43], v10, v9
	v_lshl_add_u64 v[8:9], s[76:77], 0, v[0:1]
	s_add_i32 s89, s46, s48
	s_lshl_b32 s46, s48, 6
	v_readlane_b32 s47, v254, 21
	v_add_lshl_u32 v2, s50, v7, 2
	v_mov_b32_e32 v119, v1
	v_mul_u32_u24_e32 v120, 0x1200, v5
	v_mov_b32_e32 v121, v1
	v_or_b32_e32 v125, 0x4000, v114
	v_mov_b32_e32 v115, v1
	v_mul_hi_u32_u24_e32 v123, 0x1200, v114
	v_mov_b32_e32 v122, v118
	v_bitop3_b32 v145, v144, 15, v144 bitop3:0xc
	s_and_b64 s[20:21], vcc, s[20:21]
	v_or_b32_e32 v178, 16, v114
	v_add_u32_e32 v179, 8, v114
	v_add_u32_e32 v180, 24, v114
	v_or_b32_e32 v181, 32, v114
	v_add_u32_e32 v182, 40, v114
	v_sub_u32_e32 v211, v10, v5
	s_lshl_b32 s88, s49, 6
	v_lshl_add_u64 v[128:129], v[116:117], 0, s[64:65]
	v_lshl_add_u64 v[130:131], v[8:9], 0, s[64:65]
	s_add_i32 s90, s47, s46
	v_lshl_add_u32 v212, v7, 2, s85
	v_or_b32_e32 v213, 0xffffffc0, v7
	v_lshl_add_u64 v[134:135], s[44:45], 0, v[2:3]
	v_lshlrev_b32_e32 v136, 1, v0
	v_lshlrev_b32_e32 v146, 1, v4
	v_lshlrev_b32_e32 v148, 1, v6
	s_branch .LBB0_382
	s_nop 0
	s_nop 0
	s_nop 0
	s_nop 0
	s_nop 0
	s_nop 0
	s_nop 0
	s_nop 0
	s_nop 0
	s_nop 0
	s_nop 0

; #define REP(k) for (int rep_ = 0; rep_ < (((REPMASK) >> (k)) & 1) + 1; ++rep_)
; __device__ __forceinline__ void dn_conv_token4(const P& p, int m0, int lane) {
;     const bf16_t* PRE = (const bf16_t*)(p.ws + WS_DNPRE);
;     int s0, s1;
;     if (m0 < MLAT) { s0 = m0 & ~2047; s1 = s0 + 2048; } else { s0 = MLAT + ((m0 - MLAT) & ~255); s1 = s0 + 256; }
; #pragma unroll 1
;     for (int cgp = 0; cgp < 3; ++cgp) {
;         const int col = cgp * 512 + lane * 8;
;         f32x4 w[5][2];
; #pragma unroll
;         for (int j = 0; j < 5; ++j) { w[j][0] = *(const f32x4*)(p.conv_w + j * 1536 + col); w[j][1] = *(const f32x4*)(p.conv_w + j * 1536 + col + 4); }
;         u32x4 xr[8];
; #pragma unroll
;         for (int r = 0; r < 8; ++r) { const int mm = m0 + r - 2; xr[r] = (mm >= s0 && mm < s1) ? *(const u32x4*)(PRE + (size_t)mm * 1536 + col) : (u32x4){0u, 0u, 0u, 0u}; }
;         bf16_t* dbase = (bf16_t*)(p.ws + (cgp == 0 ? WS_QN : (cgp == 1 ? WS_KN : WS_VV))) + lane * 8;
; __global__ void __launch_bounds__(NTHREADS) mega_fwd(P p) {
;     ...
;                 PH();
;                 if (ngw == 2048) {
;                     const int vcu = ((int)blockIdx.x % 8) * (G / 8) + (int)blockIdx.x / 8, gwv = vcu * 8 + wave;
;                     if (RUN(6)) REP(6) {
;                         if (gwv >= 1024) { for (int k = 0; k < 4; ++k) dn_conv_token4(q, ((gwv - 1024) * 4 + k) * 4, lane); }
;                         else if (gwv < 512) dn_conv_token4(q, (4096 + gwv) * 4, lane);
;                     }
;                 } else if (RUN(6)) REP(6) for (int m = gw * 4; m < MALL; m += ngw * 4) dn_conv_token4(q, m, lane);
.LBB0_418:
	s_cmp_eq_u32 s100, 2
	s_cbranch_scc1 .Lst_bar
	v_mov_b32_e32 v0, v1
	s_nop 0
	v_readfirstlane_b32 s2, v0
	s_load_dwordx4 s[72:75], s[92:93], s2 offset:0x60
	s_load_dwordx2 s[8:9], s[92:93], s2 offset:0x70
	s_nop 0
	s_load_dwordx2 s[2:3], s[92:93], s2 offset:0xa8
	v_readfirstlane_b32 s6, v144
	s_ashr_i32 s62, s6, 6
	v_readlane_b32 s6, v253, 58
	v_readlane_b32 s7, v253, 59
	v_and_b32_e32 v110, 63, v144
	s_andn2_b64 vcc, exec, s[6:7]
	s_mov_b64 s[6:7], -1
	s_cbranch_vccnz .LBB0_453
	s_waitcnt lgkmcnt(0)
	v_writelane_b32 v255, s8, 8
	v_readlane_b32 s6, v254, 26
	s_nop 0
	v_writelane_b32 v255, s9, 9
	v_writelane_b32 v255, s72, 10
	s_lshl_b32 s8, s62, 2
	s_add_i32 s16, s8, s6
	v_writelane_b32 v255, s73, 11
	v_writelane_b32 v255, s74, 12
	v_writelane_b32 v255, s75, 13
	s_cmpk_gt_i32 s16, 0x47ff
	s_cbranch_scc1 .LBB0_452
	s_add_u32 s18, s2, 0xfd00000
	v_and_b32_e32 v76, 15, v144
	s_addc_u32 s19, s3, 0
	v_readlane_b32 s10, v255, 8
	v_readlane_b32 s12, v255, 10
	v_lshlrev_b32_e32 v2, 2, v76
	v_mov_b32_e32 v3, v1
	v_readlane_b32 s11, v255, 9
	v_readlane_b32 s14, v255, 12
	v_readlane_b32 s15, v255, 13
	s_add_u32 s22, s2, 0xff00000
	v_lshl_add_u64 v[78:79], s[10:11], 0, v[2:3]
	v_readlane_b32 s13, v255, 11
	v_lshl_add_u64 v[80:81], s[14:15], 0, v[2:3]
	s_addc_u32 s23, s3, 0
	v_lshlrev_b32_e32 v2, 5, v110
	v_lshl_add_u64 v[82:83], s[12:13], 0, v[2:3]
	s_add_u32 s13, s2, 0xb500000
	v_readlane_b32 s9, v254, 23
	s_addc_u32 s14, s3, 0
	s_add_i32 s15, s9, s8
	v_readlane_b32 s9, v254, 24
	s_add_i32 s20, s9, s8
	s_mul_i32 s10, s16, 0xc00
	s_mul_hi_i32 s9, s16, 0xc00
	s_add_u32 s24, s2, s10
	s_addc_u32 s25, s3, s9
	v_readlane_b32 s9, v254, 25
	v_lshlrev_b32_e32 v0, 4, v110
	s_add_i32 s21, s9, s8
	v_readlane_b32 s9, v254, 27
	v_lshl_add_u64 v[74:75], s[2:3], 0, v[0:1]
	v_lshrrev_b32_e32 v77, 4, v110
	v_cmp_lt_u32_e64 s[6:7], 7, v76
	s_add_i32 s12, s9, s8
	s_branch .LBB0_422

; __device__ __forceinline__ void dn_conv_token4(const P& p, int m0, int lane) {
;     const bf16_t* PRE = (const bf16_t*)(p.ws + WS_DNPRE);
;     int s0, s1;
;     if (m0 < MLAT) { s0 = m0 & ~2047; s1 = s0 + 2048; } else { s0 = MLAT + ((m0 - MLAT) & ~255); s1 = s0 + 256; }
; #pragma unroll 1
;     for (int cgp = 0; cgp < 3; ++cgp) {
;         const int col = cgp * 512 + lane * 8;
;         f32x4 w[5][2];
; #pragma unroll
;         for (int j = 0; j < 5; ++j) { w[j][0] = *(const f32x4*)(p.conv_w + j * 1536 + col); w[j][1] = *(const f32x4*)(p.conv_w + j * 1536 + col + 4); }
;         u32x4 xr[8];
; #pragma unroll
;         for (int r = 0; r < 8; ++r) { const int mm = m0 + r - 2; xr[r] = (mm >= s0 && mm < s1) ? *(const u32x4*)(PRE + (size_t)mm * 1536 + col) : (u32x4){0u, 0u, 0u, 0u}; }
.LBB0_422:
	s_mul_i32 s9, s15, 0xc00
	s_mul_hi_i32 s8, s15, 0xc00
	s_add_u32 s26, s13, s9
	s_addc_u32 s27, s14, s8
	s_mul_i32 s9, s20, 0xc00
	s_mul_hi_i32 s8, s20, 0xc00
	s_add_u32 s28, s13, s9
	s_addc_u32 s29, s14, s8
	s_mul_i32 s9, s21, 0xc00
	s_mul_hi_i32 s8, s21, 0xc00
	s_add_u32 s30, s13, s9
	s_addc_u32 s31, s14, s8
	s_mul_i32 s9, s12, 0xc00
	s_mul_hi_i32 s8, s12, 0xc00
	s_add_u32 s34, s13, s9
	s_addc_u32 s35, s14, s8
	s_and_b32 s8, s16, 0xfffff800
	s_and_b32 s10, s16, 0x7fffff00
	s_add_i32 s9, s8, 0x800
	s_add_i32 s11, s10, 0x100
	s_cmpk_lt_i32 s16, 0x4000
	s_cselect_b32 s50, s9, s11
	s_cselect_b32 s52, s8, s10
	s_add_i32 s10, s16, -2
	s_cmp_ge_i32 s10, s52
	s_cselect_b64 s[8:9], -1, 0
	s_cmp_lt_i32 s10, s50
	s_cselect_b64 s[10:11], -1, 0
	s_and_b64 s[40:41], s[8:9], s[10:11]
	s_add_i32 s10, s16, -1
	s_cmp_ge_i32 s10, s52
	s_cselect_b64 s[8:9], -1, 0
	s_cmp_lt_i32 s10, s50
	s_cselect_b64 s[10:11], -1, 0
	s_and_b64 s[42:43], s[8:9], s[10:11]
	s_cmp_ge_i32 s16, s52
	s_cselect_b64 s[8:9], -1, 0
	s_cmp_lt_i32 s16, s50
	s_cselect_b64 s[10:11], -1, 0
	s_and_b64 s[44:45], s[8:9], s[10:11]
	s_ashr_i32 s17, s16, 31
	s_or_b32 s8, s16, 1
	s_cmp_ge_i32 s8, s52
	s_cselect_b64 s[10:11], -1, 0
	s_cmp_lt_i32 s8, s50
	s_cselect_b64 s[46:47], -1, 0
	s_and_b64 s[46:47], s[10:11], s[46:47]
	s_ashr_i32 s9, s8, 31
	s_or_b32 s10, s16, 2
	s_cmp_ge_i32 s10, s52
	s_cselect_b64 s[48:49], -1, 0
	s_cmp_lt_i32 s10, s50
	s_cselect_b64 s[72:73], -1, 0
	s_and_b64 s[48:49], s[48:49], s[72:73]
	s_ashr_i32 s11, s10, 31
	s_or_b32 s72, s16, 3
	s_cmp_ge_i32 s72, s52
	s_cselect_b64 s[74:75], -1, 0
	s_cmp_lt_i32 s72, s50
	s_cselect_b64 s[76:77], -1, 0
	s_and_b64 s[76:77], s[74:75], s[76:77]
	s_ashr_i32 s73, s72, 31
	s_add_i32 s54, s16, 4
	s_cmp_ge_i32 s54, s52
	s_cselect_b64 s[74:75], -1, 0
	s_cmp_lt_i32 s54, s50
	s_cselect_b64 s[78:79], -1, 0
	s_and_b64 s[80:81], s[74:75], s[78:79]
	s_add_i32 s54, s16, 5
	s_cmp_ge_i32 s54, s52
	s_cselect_b64 s[74:75], -1, 0
	s_cmp_lt_i32 s54, s50
	s_cselect_b64 s[78:79], -1, 0
	s_and_b64 s[82:83], s[74:75], s[78:79]
	s_lshl_b64 s[84:85], s[16:17], 10
	s_lshl_b64 s[86:87], s[8:9], 10
	s_lshl_b64 s[88:89], s[10:11], 10
	s_lshl_b64 s[90:91], s[72:73], 10
	s_mov_b64 s[92:93], 0
	s_mov_b64 s[94:95], s[24:25]
	s_branch .LBB0_424
	s_nop 0
	s_nop 0
	s_nop 0
	s_nop 0
	s_nop 0
	s_nop 0
	s_nop 0
	s_nop 0
	s_nop 0
	s_nop 0
	s_nop 0
	s_nop 0
	s_nop 0
	s_nop 0

; #define REP(k) for (int rep_ = 0; rep_ < (((REPMASK) >> (k)) & 1) + 1; ++rep_)
; #define GSYNC() do { xcd_barrier(bar); if ((REPMASK) & (1 << 20)) xcd_barrier(bar); } while (0)
; __global__ void __launch_bounds__(NTHREADS) mega_fwd(P p) {
;     ...
;                 PH();
;                 {
;                     const int vcu = (G % 8 == 0) ? ((int)blockIdx.x % 8) * (G / 8) + (int)blockIdx.x / 8 : (int)blockIdx.x;
;                     if (RUN(5)) REP(5) for (int t = vcu * 8 + wave; t < 3072; t += ngw) na_task(q, t, lane, (float*)(lds + wave * 12288));
;                 }
;                 PH();
;                 if (ngw == 2048) {
;                     const int vcu = ((int)blockIdx.x % 8) * (G / 8) + (int)blockIdx.x / 8, gwv = vcu * 8 + wave;
;                     if (RUN(6)) REP(6) {
;                         if (gwv >= 1024) { for (int k = 0; k < 4; ++k) dn_conv_token4(q, ((gwv - 1024) * 4 + k) * 4, lane); }
;                         else if (gwv < 512) dn_conv_token4(q, (4096 + gwv) * 4, lane);
;                     }
;                 } else if (RUN(6)) REP(6) for (int m = gw * 4; m < MALL; m += ngw * 4) dn_conv_token4(q, m, lane);
;                 GSYNC();
.LBB0_521:
	s_cmp_eq_u32 s100, 1
	s_cbranch_scc0 .Lst_bar
	s_mov_b32 s100, 2
	v_readlane_b32 s92, v254, 54
	v_readlane_b32 s93, v254, 55
	v_mov_b32_e32 v0, v1
	s_mov_b64 exec, -1
	s_branch .Lst_na

; __device__ __forceinline__ void dn_prep_task(const P& p, int task, unsigned char* sm, int tid) {
;     const int h = task & 3, bc = task >> 2, ck = bc % 36, b = bc / 36;
;     const int m0 = ck < 4 ? MLAT + b * TCTX + ck * 64 : b * TLAT + (ck - 4) * 64;
;     const int wave = tid >> 6, lane = tid & 63, dir = tid >> 8, t2 = tid & 255;
;     bf16_t* kn_s = (bf16_t*)sm;
;     bf16_t* qn_s = kn_s + 64 * 136;
;     float* KK = (float*)(sm + 34816);
;     float* QK = KK + 64 * 65;
;     float* gc_s = (float*)(sm + 68096);
;     float* be_s = gc_s + 128;
;     float* Ls = be_s + 128;
;     bf16_t* v_s = (bf16_t*)(sm + 101888);
;     {
;         const int r = tid >> 3, c16 = (tid & 7) * 16;
;         const bf16_t* ks = (const bf16_t*)(p.ws + WS_KN) + (size_t)(m0 + r) * 512 + h * 128 + c16;
;         const bf16_t* qs = (const bf16_t*)(p.ws + WS_QN) + (size_t)(m0 + r) * 512 + h * 128 + c16;
;         *(u32x4*)(kn_s + r * 136 + c16) = *(const u32x4*)ks; *(u32x4*)(kn_s + r * 136 + c16 + 8) = *(const u32x4*)(ks + 8);
;         *(u32x4*)(qn_s + r * 136 + c16) = *(const u32x4*)qs; *(u32x4*)(qn_s + r * 136 + c16 + 8) = *(const u32x4*)(qs + 8);
;         const bf16_t* vs = (const bf16_t*)(p.ws + WS_VV) + (size_t)(m0 + r) * 512 + h * 128 + c16;
;         *(u32x4*)(v_s + r * 136 + c16) = *(const u32x4*)vs; *(u32x4*)(v_s + r * 136 + c16 + 8) = *(const u32x4*)(vs + 8);
;     }
;     if (t2 < 64) {
;         const int tok = dir ? 63 - t2 : t2;
;         const float* gb = (const float*)(p.ws + WS_GB) + (size_t)(m0 + tok) * 16;
;         float gv = gb[dir * 4 + h]; const float bv = gb[8 + dir * 4 + h];
; #pragma unroll
;         for (int o = 1; o < 64; o <<= 1) { const float v = __shfl_up(gv, o); if (lane >= o) gv += v; }
;         gc_s[dir * 64 + t2] = gv; be_s[dir * 64 + t2] = bv;
;     }
;     __syncthreads();
;     {
;         const int which = wave >> 2, it = wave & 3, fr = lane & 15, g = lane >> 4;
;         const bf16_t* As = which ? qn_s : kn_s; float* Out = which ? QK : KK;
;         bf16x8 a[4];
; #pragma unroll
;         for (int ks = 0; ks < 4; ++ks) a[ks] = *(const bf16x8*)(As + (it * 16 + fr) * 136 + ks * 32 + g * 8);
; #pragma unroll
;         for (int jt = 0; jt < 4; ++jt) {
;             f32x4 acc = {0.f, 0.f, 0.f, 0.f};
; #pragma unroll
.LBB0_569:
	s_or_b64 exec, exec, s[2:3]
	v_readlane_b32 s2, v253, 62
	v_mov_b32_e32 v0, v1
	v_readlane_b32 s3, v253, 63
	s_waitcnt lgkmcnt(0)
	s_barrier
	s_andn2_b64 vcc, exec, s[2:3]
	v_readfirstlane_b32 s2, v0
	s_cbranch_vccnz .LBB0_665
	v_readlane_b32 s6, v254, 54
	v_readlane_b32 s7, v254, 55
	s_load_dwordx2 s[44:45], s[6:7], s2 offset:0xa8
	s_movk_i32 s1, 0xff
	v_cmp_lt_u32_e64 s[6:7], s1, v144
	v_lshlrev_b32_e32 v88, 4, v144
	v_ashrrev_i32_e32 v9, 3, v144
	s_waitcnt lgkmcnt(0)
	s_add_u32 s46, s44, 0x11300000
	s_addc_u32 s47, s45, 0
	s_add_u32 s48, s44, 0x10100000
	s_addc_u32 s49, s45, 0
	s_add_u32 s28, s44, 0x12500000
	s_addc_u32 s29, s45, 0
	v_writelane_b32 v255, s6, 10
	v_and_b32_e32 v2, 0x70, v88
	s_movk_i32 s3, 0x110
	v_writelane_b32 v255, s7, 11
	s_add_u32 s6, s44, 0xff00000
	v_mul_lo_u32 v0, v9, s3
	v_lshlrev_b32_e32 v3, 1, v2
	v_readlane_b32 s42, v254, 43
	s_addc_u32 s7, s45, 0
	v_add3_u32 v89, 0, v0, v3
	v_add3_u32 v90, s42, v0, v3
	v_and_b32_e32 v0, 63, v144
	v_writelane_b32 v255, s6, 14
	v_and_b32_e32 v8, 0xff, v144
	s_movk_i32 s2, 0x100
	v_writelane_b32 v255, s7, 15
	v_cmp_eq_u32_e64 s[6:7], 0, v0
	v_cmp_gt_u32_e32 vcc, s2, v144
	v_sub_u32_e32 v3, 63, v8
	v_writelane_b32 v255, s6, 16
	v_cndmask_b32_e32 v91, v3, v8, vcc
	v_and_b32_e32 v3, 0xffffff00, v144
	v_writelane_b32 v255, s7, 17
	v_cmp_gt_u32_e64 s[6:7], 2, v0
	v_lshlrev_b32_e32 v6, 2, v8
	v_readlane_b32 s1, v254, 44
	v_writelane_b32 v255, s6, 18
	v_readlane_b32 s50, v254, 45
	v_readlane_b32 s2, v254, 46
	v_writelane_b32 v255, s7, 19
	v_cmp_gt_u32_e64 s[6:7], 4, v0
	s_waitcnt vmcnt(1)
	v_mov_b32_e32 v5, s2
	v_lshrrev_b32_e32 v7, 2, v144
	v_writelane_b32 v255, s6, 20
	v_cndmask_b32_e64 v5, v5, 0, vcc
	v_readlane_b32 s2, v254, 48
	v_writelane_b32 v255, s7, 21
	v_cmp_gt_u32_e64 s[6:7], 8, v0
	v_bfe_u32 v22, v144, 2, 6
	v_ashrrev_i32_e32 v4, 8, v144
	v_writelane_b32 v255, s6, 22
	v_bitop3_b32 v14, v88, 62, 48 bitop3:0x6c
	v_bitop3_b32 v15, v88, 61, 48 bitop3:0x6c
	v_writelane_b32 v255, s7, 23
	v_cmp_gt_u32_e64 s[6:7], 16, v0
	v_bitop3_b32 v13, v88, 63, 48 bitop3:0x6c
	v_bitop3_b32 v20, v88, 60, 48 bitop3:0x6c
	v_writelane_b32 v255, s6, 24
	v_bitop3_b32 v23, v88, 59, 48 bitop3:0x6c
	v_bitop3_b32 v31, v88, 58, 48 bitop3:0x6c
	v_writelane_b32 v255, s7, 25
	v_cmp_gt_u32_e64 s[6:7], 32, v0
	v_or_b32_e32 v0, v3, v6
	v_add_u32_e32 v92, s1, v0
	v_add_u32_e32 v93, s50, v0
	v_and_b32_e32 v0, 15, v144
	v_and_or_b32 v11, v7, 48, v0
	v_mad_u32_u24 v24, v11, s3, v5
	v_mov_b32_e32 v5, s2
	v_readlane_b32 s2, v254, 47
	v_and_b32_e32 v7, 60, v7
	v_mul_u32_u24_e32 v29, 0x104, v7
	v_mov_b32_e32 v11, s2
	v_cndmask_b32_e32 v5, v5, v11, vcc
	v_readlane_b32 s2, v254, 49
	v_xor_b32_e32 v7, 63, v22
	v_writelane_b32 v255, s6, 26
	v_lshl_add_u32 v27, v0, 2, v5
	v_mul_u32_u24_e32 v28, 0x110, v0
	v_lshl_add_u32 v94, v4, 14, s2
	v_and_b32_e32 v0, 48, v88
	v_cndmask_b32_e32 v7, v7, v22, vcc
	s_movk_i32 s2, 0x104
	v_writelane_b32 v255, s7, 27
	v_lshlrev_b32_e32 v11, 8, v22
	v_mad_u32_u24 v12, v7, s2, 0
	v_cmp_gt_u32_e64 s[2:3], v22, v0
	v_lshlrev_b32_e32 v17, 2, v0
	v_add3_u32 v96, v94, v11, v17
	v_writelane_b32 v255, s2, 8
	v_or_b32_e32 v11, 1, v0
	v_or_b32_e32 v21, 4, v0
	v_writelane_b32 v255, s3, 9
	v_cmp_gt_u32_e64 s[2:3], v22, v11
	v_cndmask_b32_e32 v11, v14, v11, vcc
	v_or_b32_e32 v14, 2, v0
	v_writelane_b32 v255, s2, 28
	v_or_b32_e32 v30, 5, v0
	v_or_b32_e32 v32, 6, v0
	v_writelane_b32 v255, s3, 29
	v_cmp_gt_u32_e64 s[2:3], v22, v14
	v_cndmask_b32_e32 v14, v15, v14, vcc
	v_or_b32_e32 v15, 3, v0
	v_writelane_b32 v255, s2, 30
	v_or_b32_e32 v34, 7, v0
	v_or_b32_e32 v36, 8, v0
	v_writelane_b32 v255, s3, 31
	v_cmp_gt_u32_e64 s[2:3], v22, v15
	v_or_b32_e32 v38, 9, v0
	v_or_b32_e32 v40, 10, v0
	v_writelane_b32 v255, s2, 32
	v_or_b32_e32 v42, 11, v0
	v_or_b32_e32 v44, 12, v0
	v_writelane_b32 v255, s3, 33
	v_cmp_gt_u32_e64 s[2:3], v22, v21
	v_or_b32_e32 v46, 13, v0
	v_or_b32_e32 v48, 14, v0
	v_writelane_b32 v255, s2, 34
	v_bitop3_b32 v33, v88, 57, 48 bitop3:0x6c
	v_bitop3_b32 v35, v88, 56, 48 bitop3:0x6c
	v_writelane_b32 v255, s3, 35
	v_cmp_gt_u32_e64 s[2:3], v22, v30
	v_bitop3_b32 v37, v88, 55, 48 bitop3:0x6c
	v_bitop3_b32 v39, v88, 54, 48 bitop3:0x6c
	v_writelane_b32 v255, s2, 36
	v_bitop3_b32 v41, v88, 53, 48 bitop3:0x6c
	v_bitop3_b32 v43, v88, 52, 48 bitop3:0x6c
	v_writelane_b32 v255, s3, 37
	v_cmp_gt_u32_e64 s[2:3], v22, v32
	v_bitop3_b32 v45, v88, 51, 48 bitop3:0x6c
	v_bitop3_b32 v47, v88, 50, 48 bitop3:0x6c
	v_writelane_b32 v255, s2, 38
	v_bitop3_b32 v49, v88, 49, 48 bitop3:0x6c
	v_or_b32_e32 v50, 15, v0
	v_writelane_b32 v255, s3, 39
	v_cmp_gt_u32_e64 s[2:3], v22, v34
	v_bitop3_b32 v51, v88, 48, v88 bitop3:0xc
	v_cndmask_b32_e32 v13, v13, v0, vcc
	v_writelane_b32 v255, s2, 40
	v_cndmask_b32_e32 v15, v20, v15, vcc
	v_cndmask_b32_e32 v21, v23, v21, vcc
	v_writelane_b32 v255, s3, 41
	v_cmp_gt_u32_e64 s[2:3], v22, v36
	v_cndmask_b32_e32 v30, v31, v30, vcc
	v_cndmask_b32_e32 v32, v33, v32, vcc
	v_writelane_b32 v255, s2, 42
	v_cndmask_b32_e32 v34, v35, v34, vcc
	v_cndmask_b32_e32 v36, v37, v36, vcc
	v_writelane_b32 v255, s3, 43
	v_cmp_gt_u32_e64 s[2:3], v22, v38
	v_cndmask_b32_e32 v38, v39, v38, vcc
	v_cmp_gt_u32_e64 s[86:87], v22, v50
	v_writelane_b32 v255, s2, 44
	v_cndmask_b32_e32 v50, v51, v50, vcc
; __device__ __forceinline__ void dn_prep_task(const P& p, int task, unsigned char* sm, int tid) {
;     ...
;     const float* gc = gc_s + dir * 64; const float* be = be_s + dir * 64; float* L = Ls + dir * 4096;
;     const size_t dt = (size_t)task * 2 + dir;
;     {
;         const int cp = t2 >> 2, s0 = (t2 & 3) * 16; const int ctok = dir ? 63 - cp : cp; const float gcc = gc[cp], bec = be[cp];
; #pragma unroll
;         for (int i = 0; i < 16; ++i) { const int sp = s0 + i, stok = dir ? 63 - sp : sp; float v = 0.f; if (cp > sp) v = bec * KK[ctok * 65 + stok] * __expf(gcc - gc[sp]); L[cp * 64 + sp] = v; }
;         const int c = t2 >> 2, c_p = dir ? 63 - c : c; const float gq = gc[c_p];
;         float qv[16];
; #pragma unroll
;         for (int i = 0; i < 16; ++i) { const int s = s0 + i, s_p = dir ? 63 - s : s; qv[i] = (c_p >= s_p) ? QK[c * 65 + s] * SCALE_DK * __expf(gq - gc[s_p]) : 0.f; }
	v_lshlrev_b32_e32 v16, 2, v13
	v_writelane_b32 v255, s3, 45
	v_cmp_gt_u32_e64 s[2:3], v22, v40
	v_cndmask_b32_e32 v40, v41, v40, vcc
	v_lshlrev_b32_e32 v18, 2, v11
	v_writelane_b32 v255, s2, 46
	v_lshlrev_b32_e32 v19, 2, v14
	v_lshlrev_b32_e32 v20, 2, v15
	v_writelane_b32 v255, s3, 47
	v_cmp_gt_u32_e64 s[2:3], v22, v42
	v_cndmask_b32_e32 v42, v43, v42, vcc
	v_lshlrev_b32_e32 v23, 2, v21
	v_writelane_b32 v255, s2, 48
	v_lshlrev_b32_e32 v31, 2, v30
	v_lshlrev_b32_e32 v33, 2, v32
	v_writelane_b32 v255, s3, 49
	v_cmp_gt_u32_e64 s[2:3], v22, v44
	v_cndmask_b32_e32 v44, v45, v44, vcc
	v_lshlrev_b32_e32 v35, 2, v34
	v_writelane_b32 v255, s2, 50
	v_lshlrev_b32_e32 v37, 2, v36
	v_lshlrev_b32_e32 v39, 2, v38
	v_writelane_b32 v255, s3, 51
	v_cmp_gt_u32_e64 s[2:3], v22, v46
	v_cndmask_b32_e32 v46, v47, v46, vcc
	v_lshlrev_b32_e32 v41, 2, v40
	v_writelane_b32 v255, s2, 52
	v_lshlrev_b32_e32 v43, 2, v42
	v_lshlrev_b32_e32 v45, 2, v44
	v_writelane_b32 v255, s3, 53
	v_cmp_gt_u32_e64 s[2:3], v22, v48
	v_cndmask_b32_e32 v48, v49, v48, vcc
	v_lshlrev_b32_e32 v47, 2, v46
	v_writelane_b32 v255, s2, 54
	v_lshlrev_b32_e32 v49, 2, v48
	v_lshlrev_b32_e32 v51, 2, v50
	v_writelane_b32 v255, s3, 55
	v_cmp_eq_u32_e64 s[2:3], 0, v8
	v_cmp_ge_u32_e64 s[8:9], v7, v32
	v_mul_u32_u24_e32 v32, 0x110, v0
	v_writelane_b32 v255, s2, 56
	v_lshlrev_b32_e32 v0, 1, v8
	v_readlane_b32 s76, v254, 28
	v_writelane_b32 v255, s3, 57
	s_movk_i32 s2, 0x80
	v_ashrrev_i32_e32 v5, 31, v4
	v_add_u32_e32 v95, v12, v16
	v_add_u32_e32 v97, v12, v18
	v_add_u32_e32 v98, v12, v19
	v_add_u32_e32 v99, v12, v20
	v_add_u32_e32 v100, v12, v23
	v_add_u32_e32 v101, v12, v31
	v_add_u32_e32 v102, v12, v33
	v_add_u32_e32 v103, v12, v35
	v_add_u32_e32 v104, v12, v37
	v_add_u32_e32 v105, v12, v39
	v_add_u32_e32 v106, v12, v41
	v_add_u32_e32 v107, v12, v43
	v_add_u32_e32 v108, v12, v45
	v_add_u32_e32 v109, v12, v47
	v_add_u32_e32 v110, v12, v49
	v_add_u32_e32 v111, v12, v51
	v_mul_u32_u24_e32 v12, 0x104, v22
	v_cmp_gt_u32_e64 s[30:31], s2, v8
	s_movk_i32 s2, 0x7f
	v_add_u32_e32 v113, 0, v0
	v_add_u32_e32 v115, s42, v0
	v_add_u32_e32 v116, v94, v0
	v_lshlrev_b32_e32 v0, 6, v144
	v_add_u32_e32 v119, s1, v3
	v_readlane_b32 s77, v254, 29
	v_readlane_b32 s72, v254, 38
	v_cmp_ge_u32_e64 s[88:89], v7, v13
	v_add3_u32 v112, 0, v12, v17
	v_cmp_ge_u32_e64 s[90:91], v7, v11
	v_cmp_ge_u32_e64 s[84:85], v7, v21
	v_ashrrev_i32_e32 v11, 2, v144
	v_cmp_lt_u32_e64 s[34:35], s2, v8
	v_add_u32_e32 v128, v119, v20
	v_lshl_add_u64 v[12:13], v[0:1], 1, s[76:77]
	v_and_b32_e32 v0, 3, v144
	v_readlane_b32 s2, v254, 32
	v_lshlrev_b64 v[20:21], 10, v[4:5]
	v_readlane_b32 s73, v254, 39
	v_lshlrev_b32_e32 v10, 2, v4
	v_cmp_ge_u32_e64 s[92:93], v7, v14
	v_cmp_ge_u32_e64 s[94:95], v7, v15
	v_cmp_ge_u32_e64 s[6:7], v7, v30
	v_cmp_ge_u32_e64 s[10:11], v7, v34
	v_cmp_ge_u32_e64 s[12:13], v7, v36
	v_cmp_ge_u32_e64 s[14:15], v7, v38
	v_cmp_ge_u32_e64 s[16:17], v7, v40
	v_cmp_ge_u32_e64 s[18:19], v7, v42
	v_cmp_ge_u32_e64 s[20:21], v7, v44
	v_cmp_ge_u32_e64 s[22:23], v7, v46
	v_cmp_ge_u32_e64 s[24:25], v7, v48
	v_cmp_ge_u32_e64 s[26:27], v7, v50
	v_lshlrev_b32_e32 v14, 6, v11
	v_lshl_add_u32 v124, v7, 2, v119
	v_add_u32_e32 v126, v119, v18
	v_add_u32_e32 v127, v119, v19
	v_lshlrev_b32_e32 v0, 5, v0
	v_readlane_b32 s3, v254, 33
	v_lshl_add_u64 v[18:19], s[72:73], 0, v[20:21]
	v_mov_b32_e32 v7, v1
	v_lshlrev_b64 v[4:5], 13, v[4:5]
	v_and_b32_e32 v25, 48, v144
	v_ashrrev_i32_e32 v15, 31, v14
	v_add_u32_e32 v123, v119, v17
	v_add_u32_e32 v125, v119, v16
	v_lshl_add_u64 v[16:17], s[2:3], 0, v[0:1]
	v_lshl_add_u64 v[18:19], v[18:19], 0, v[6:7]
	v_readlane_b32 s72, v254, 40
	v_lshl_add_u64 v[4:5], s[2:3], 0, v[4:5]
	v_lshlrev_b32_e32 v6, 7, v22
	v_add_u32_e32 v26, 0, v25
	v_lshl_add_u32 v30, v11, 1, 0
	s_add_u32 s42, s44, 0x7f00000
	v_add_u32_e32 v120, s50, v3
	v_and_b32_e32 v3, 0xfc, v144
	v_lshl_add_u64 v[14:15], v[14:15], 1, v[16:17]
	v_lshlrev_b32_e32 v16, 7, v8
	v_mov_b32_e32 v17, v1
	v_readlane_b32 s73, v254, 41
	v_lshl_add_u64 v[4:5], v[4:5], 0, v[6:7]
	v_cmp_gt_u32_e64 s[40:41], 64, v8
	v_add_u32_e32 v114, 0xffffff00, v113
	v_add_u32_e32 v117, 0xffffff00, v116
	s_addc_u32 s43, s45, 0
	v_lshlrev_b32_e32 v118, 4, v8
	v_add_u32_e32 v121, v119, v3
	v_add_u32_e32 v122, v120, v3
	v_add_u32_e32 v129, v119, v23
	v_add_u32_e32 v130, v119, v31
	v_add_u32_e32 v131, v119, v33
	v_add_u32_e32 v132, v119, v35
	v_add_u32_e32 v133, v119, v37
	v_add_u32_e32 v134, v119, v39
	v_add_u32_e32 v135, v119, v41
	v_add_u32_e32 v136, v119, v43
	v_add_u32_e32 v137, v119, v45
	v_add_u32_e32 v143, v119, v47
	v_add_u32_e32 v145, v119, v49
	v_add_u32_e32 v146, v119, v51
	v_lshl_add_u32 v147, v91, 2, v119
	v_ashrrev_i32_e32 v11, 31, v10
	v_lshl_add_u64 v[16:17], s[76:77], 0, v[16:17]
	v_lshl_add_u64 v[20:21], s[72:73], 0, v[20:21]
	v_lshl_add_u64 v[22:23], v[4:5], 0, v[0:1]
	v_lshlrev_b32_e32 v0, 1, v2
	v_add_u32_e32 v148, v24, v25
	v_add_u32_e32 v149, v26, v28
	v_add_u32_e32 v150, v27, v29
	v_add_u32_e32 v151, v30, v32
	v_lshlrev_b32_e32 v24, 4, v8
	v_readlane_b32 s2, v254, 56
	v_readlane_b32 s3, v254, 57
	s_branch .LBB0_573
	s_nop 0
	s_nop 0
	s_nop 0
	s_nop 0
	s_nop 0
	s_nop 0
	s_nop 0
	s_nop 0
	s_nop 0
	s_nop 0
	s_nop 0
	s_nop 0
	s_nop 0
